# v25 + G1 item loads all issued up front (prefetch registers, counted waits)
# speedup vs baseline: 1.0149x; 1.0029x over previous
; __device__ __forceinline__ float bf1(bf16_t b) { return __uint_as_float(((unsigned)b) << 16); }
; __device__ __forceinline__ void gla_g1(const Params& P, unsigned char* lds) {
;     ...
;         { const int dk = tid & 127, tq = tid >> 7; const float blast = bsh[63 * 128 + dk]; float ke[16];
;             bf16_t kraw[16];
; #pragma unroll
;             for (int i = 0; i < 16; ++i) { const int t = tq * 16 + i, tc = t < I.L ? t : I.L - 1; kraw[i] = kg[(size_t)(I.row0 + tc) * KEYD + I.h * DK + dk]; }
; #pragma unroll
;             for (int i = 0; i < 16; ++i) { const int t = tq * 16 + i; const float kv = bf1(kraw[i]) * __expf(blast - bsh[t * 128 + dk]); ke[i] = t < I.L ? kv : 0.f; }
.Lg1_bskip:
	s_mov_b64 exec, s[98:99]
	v_lshl_add_u64 v[4:5], v[0:1], 0, v[4:5]
	s_waitcnt vmcnt(4)
	v_mov_b32_e32 v18, v212
	v_mov_b32_e32 v19, v213
	v_min_i32_e32 v6, s48, v97
	v_min_i32_e32 v10, s48, v101
	v_add_u32_e32 v6, s82, v6
	v_add_u32_e32 v10, s82, v10
	v_ashrrev_i32_e32 v7, 31, v6
	v_ashrrev_i32_e32 v11, 31, v10
	v_lshlrev_b64 v[6:7], 10, v[6:7]
	v_lshlrev_b64 v[10:11], 10, v[10:11]
	v_min_i32_e32 v12, s48, v102
	v_lshl_add_u64 v[6:7], v[0:1], 0, v[6:7]
	v_min_i32_e32 v8, s48, v98
	v_lshl_add_u64 v[10:11], v[0:1], 0, v[10:11]
	v_add_u32_e32 v12, s82, v12
	v_ashrrev_i32_e32 v13, 31, v12
	v_mov_b32_e32 v20, v214
	v_mov_b32_e32 v24, v218
	v_add_u32_e32 v2, s82, v8
	v_min_i32_e32 v4, s48, v99
	v_min_i32_e32 v8, s48, v100
	v_add_u32_e32 v4, s82, v4
	v_add_u32_e32 v8, s82, v8
	v_lshlrev_b64 v[6:7], 10, v[12:13]
	v_min_i32_e32 v12, s48, v103
	v_ashrrev_i32_e32 v3, 31, v2
	v_ashrrev_i32_e32 v5, 31, v4
	v_ashrrev_i32_e32 v9, 31, v8
	v_add_u32_e32 v12, s82, v12
	v_lshlrev_b64 v[2:3], 10, v[2:3]
	v_lshlrev_b64 v[4:5], 10, v[4:5]
	v_lshlrev_b64 v[8:9], 10, v[8:9]
	v_ashrrev_i32_e32 v13, 31, v12
	v_lshl_add_u64 v[2:3], v[0:1], 0, v[2:3]
	v_lshl_add_u64 v[4:5], v[0:1], 0, v[4:5]
	v_lshl_add_u64 v[8:9], v[0:1], 0, v[8:9]
	v_lshlrev_b64 v[12:13], 10, v[12:13]
	v_mov_b32_e32 v21, v215
	v_mov_b32_e32 v22, v216
	v_mov_b32_e32 v23, v217
	v_lshl_add_u64 v[2:3], v[0:1], 0, v[12:13]
	v_min_i32_e32 v12, s48, v104
	v_add_u32_e32 v4, s82, v12
	v_min_i32_e32 v12, s48, v105
	v_add_u32_e32 v12, s82, v12
	v_ashrrev_i32_e32 v13, 31, v12
	v_lshlrev_b64 v[12:13], 10, v[12:13]
	v_lshl_add_u64 v[8:9], v[0:1], 0, v[12:13]
	v_min_i32_e32 v12, s48, v106
	v_add_u32_e32 v10, s82, v12
	v_min_i32_e32 v12, s48, v107
	v_add_u32_e32 v12, s82, v12
	v_ashrrev_i32_e32 v13, 31, v12
	v_lshl_add_u64 v[6:7], v[0:1], 0, v[6:7]
	v_lshlrev_b64 v[12:13], 10, v[12:13]
	v_mov_b32_e32 v25, v219
	v_mov_b32_e32 v26, v220
	v_lshl_add_u64 v[6:7], v[0:1], 0, v[12:13]
	v_min_i32_e32 v12, s48, v108
	v_add_u32_e32 v2, s82, v12
	v_ashrrev_i32_e32 v3, 31, v2
	v_lshlrev_b64 v[2:3], 10, v[2:3]
	v_ashrrev_i32_e32 v5, 31, v4
	v_lshl_add_u64 v[12:13], v[0:1], 0, v[2:3]
	v_min_i32_e32 v2, s48, v109
	v_lshlrev_b64 v[4:5], 10, v[4:5]
	v_add_u32_e32 v2, s82, v2
	v_lshl_add_u64 v[4:5], v[0:1], 0, v[4:5]
	v_ashrrev_i32_e32 v3, 31, v2
	v_lshlrev_b64 v[14:15], 10, v[2:3]
	ds_read_b32 v2, v114 offset:4096
	ds_read_b32 v3, v113 offset:4096
	v_mov_b32_e32 v27, v221
	v_min_i32_e32 v16, s48, v110
	v_ashrrev_i32_e32 v11, 31, v10
	v_add_u32_e32 v16, s82, v16
	v_lshlrev_b64 v[10:11], 10, v[10:11]
	v_ashrrev_i32_e32 v17, 31, v16
	v_lshl_add_u64 v[10:11], v[0:1], 0, v[10:11]
	v_mov_b32_e32 v8, v222
	v_lshlrev_b64 v[4:5], 10, v[16:17]
	v_lshl_add_u64 v[14:15], v[0:1], 0, v[14:15]
	v_lshl_add_u64 v[0:1], v[0:1], 0, v[4:5]
	v_mov_b32_e32 v5, v223
	s_nop 0
	v_mov_b32_e32 v6, v224
	s_waitcnt lgkmcnt(0)
	v_sub_f32_e32 v3, v2, v3
	v_mul_f32_e32 v3, 0x3fb8aa3b, v3
	v_exp_f32_e32 v3, v3
	v_lshlrev_b32_e32 v4, 16, v18
	v_mul_f32_e32 v3, v3, v4
	v_lshlrev_b32_e32 v4, 16, v19
	ds_read_b32 v7, v133 offset:4096
	ds_read_b32 v9, v134 offset:4096
	ds_read_b32 v10, v135 offset:4096
	ds_read_b32 v11, v136 offset:4096
	ds_read_b32 v16, v137 offset:4096
	ds_read_b32 v17, v138 offset:4096
	ds_read_b32 v18, v139 offset:4096
	ds_read_b32 v19, v140 offset:4096
	v_mov_b32_e32 v12, v225
	s_waitcnt lgkmcnt(7)
	v_sub_f32_e32 v7, v2, v7
	v_mov_b32_e32 v0, v227
	v_mul_f32_e32 v7, 0x3fb8aa3b, v7
	v_mov_b32_e32 v13, v226
	s_waitcnt lgkmcnt(6)
	v_sub_f32_e32 v9, v2, v9
	v_exp_f32_e32 v7, v7
	v_mul_f32_e32 v9, 0x3fb8aa3b, v9
	v_exp_f32_e32 v9, v9
	s_waitcnt lgkmcnt(2)
; __device__ __forceinline__ unsigned cvt_pk_bf16(float lo, float hi) { unsigned r; asm volatile("v_cvt_pk_bf16_f32 %0, %1, %2" : "=v"(r) : "v"(lo), "v"(hi)); return r; }
; __device__ __forceinline__ float bf1(bf16_t b) { return __uint_as_float(((unsigned)b) << 16); }
; __device__ __forceinline__ void gla_g1(const Params& P, unsigned char* lds) {
;     ...
;             for (int i = 0; i < 16; ++i) { const int t = tq * 16 + i; const float kv = bf1(kraw[i]) * __expf(blast - bsh[t * 128 + dk]); ke[i] = t < I.L ? kv : 0.f; }
;             u32x4 w0, w1; w0.x = cvt_pk_bf16(ke[0], ke[1]); w0.y = cvt_pk_bf16(ke[2], ke[3]); w0.z = cvt_pk_bf16(ke[4], ke[5]); w0.w = cvt_pk_bf16(ke[6], ke[7]);
;             w1.x = cvt_pk_bf16(ke[8], ke[9]); w1.y = cvt_pk_bf16(ke[10], ke[11]); w1.z = cvt_pk_bf16(ke[12], ke[13]); w1.w = cvt_pk_bf16(ke[14], ke[15]);
;             *(u32x4*)(kT + dk * 72 + tq * 16) = w0; *(u32x4*)(kT + dk * 72 + tq * 16 + 8) = w1;
;             if (tq == 0) dec[(size_t)it * 128 + dk] = __expf(blast); }
	v_sub_f32_e32 v14, v2, v17
	v_mul_f32_e32 v4, v7, v4
	v_lshlrev_b32_e32 v7, 16, v20
	v_mul_f32_e32 v7, v9, v7
	v_sub_f32_e32 v9, v2, v10
	v_mul_f32_e32 v9, 0x3fb8aa3b, v9
	v_sub_f32_e32 v10, v2, v11
	v_exp_f32_e32 v9, v9
	v_mul_f32_e32 v10, 0x3fb8aa3b, v10
	v_exp_f32_e32 v10, v10
	v_sub_f32_e32 v11, v2, v16
	v_mul_f32_e32 v11, 0x3fb8aa3b, v11
	v_exp_f32_e32 v11, v11
	v_mul_f32_e32 v14, 0x3fb8aa3b, v14
	s_waitcnt lgkmcnt(1)
	v_sub_f32_e32 v15, v2, v18
	v_exp_f32_e32 v14, v14
	v_lshlrev_b32_e32 v1, 16, v21
	v_mul_f32_e32 v1, v9, v1
	v_lshlrev_b32_e32 v9, 16, v22
	v_mul_f32_e32 v9, v10, v9
	v_lshlrev_b32_e32 v10, 16, v23
	v_mul_f32_e32 v15, 0x3fb8aa3b, v15
	s_waitcnt lgkmcnt(0)
	v_sub_f32_e32 v16, v2, v19
	ds_read_b32 v17, v141 offset:4096
	ds_read_b32 v18, v142 offset:4096
	ds_read_b32 v19, v143 offset:4096
	ds_read_b32 v20, v144 offset:4096
	ds_read_b32 v21, v145 offset:4096
	ds_read_b32 v22, v146 offset:4096
	ds_read_b32 v23, v147 offset:4096
	v_exp_f32_e32 v15, v15
	v_mul_f32_e32 v16, 0x3fb8aa3b, v16
	s_waitcnt lgkmcnt(6)
	v_sub_f32_e32 v17, v2, v17
	v_exp_f32_e32 v16, v16
	v_mul_f32_e32 v17, 0x3fb8aa3b, v17
	v_mul_f32_e32 v10, v11, v10
	v_lshlrev_b32_e32 v11, 16, v24
	v_exp_f32_e32 v17, v17
	v_mul_f32_e32 v11, v14, v11
	v_cndmask_b32_e64 v4, 0, v4, s[16:17]
	v_lshlrev_b32_e32 v14, 16, v25
	v_mul_f32_e32 v14, v15, v14
	v_lshlrev_b32_e32 v15, 16, v26
	v_mul_f32_e32 v15, v16, v15
	v_cndmask_b32_e64 v7, 0, v7, s[18:19]
	v_cndmask_b32_e32 v3, 0, v3, vcc
	v_cndmask_b32_e64 v1, 0, v1, s[20:21]
	v_cndmask_b32_e64 v9, 0, v9, s[22:23]
	v_cndmask_b32_e64 v10, 0, v10, s[24:25]
	v_cndmask_b32_e64 v11, 0, v11, s[26:27]
	v_cndmask_b32_e64 v14, 0, v14, s[28:29]
	v_cvt_pk_bf16_f32 v4, v3, v4
	v_cndmask_b32_e64 v15, 0, v15, s[30:31]
	v_lshlrev_b32_e32 v16, 16, v27
	v_mul_f32_e32 v16, v17, v16
	s_waitcnt lgkmcnt(5)
	v_sub_f32_e32 v17, v2, v18
	s_waitcnt lgkmcnt(4)
	v_sub_f32_e32 v18, v2, v19
	v_mul_f32_e32 v18, 0x3fb8aa3b, v18
	v_exp_f32_e32 v18, v18
	v_mul_f32_e32 v17, 0x3fb8aa3b, v17
	v_exp_f32_e32 v17, v17
	v_lshlrev_b32_e32 v8, 16, v8
	v_cndmask_b32_e64 v16, 0, v16, s[34:35]
	v_lshlrev_b32_e32 v5, 16, v5
	v_mul_f32_e32 v5, v18, v5
	v_cndmask_b32_e64 v18, 0, v5, s[38:39]
	v_lshlrev_b32_e32 v5, 16, v6
	s_waitcnt lgkmcnt(3)
	v_sub_f32_e32 v6, v2, v20
	v_mul_f32_e32 v8, v17, v8
	v_mul_f32_e32 v6, 0x3fb8aa3b, v6
	v_cndmask_b32_e64 v17, 0, v8, s[36:37]
	v_exp_f32_e32 v6, v6
	s_waitcnt lgkmcnt(2)
	v_sub_f32_e32 v8, v2, v21
	v_mul_f32_e32 v8, 0x3fb8aa3b, v8
	v_exp_f32_e32 v8, v8
	v_mul_f32_e32 v5, v6, v5
	v_cndmask_b32_e64 v19, 0, v5, s[40:41]
	v_lshlrev_b32_e32 v5, 16, v12
	s_waitcnt lgkmcnt(1)
	v_sub_f32_e32 v6, v2, v22
	v_mul_f32_e32 v5, v8, v5
	v_mul_f32_e32 v6, 0x3fb8aa3b, v6
	s_waitcnt lgkmcnt(0)
	v_sub_f32_e32 v8, v2, v23
	v_exp_f32_e32 v6, v6
	v_mul_f32_e32 v8, 0x3fb8aa3b, v8
	v_exp_f32_e32 v8, v8
	v_cndmask_b32_e64 v12, 0, v5, s[42:43]
	v_lshlrev_b32_e32 v5, 16, v13
	v_mul_f32_e32 v5, v6, v5
	v_lshlrev_b32_e32 v0, 16, v0
	v_cndmask_b32_e64 v13, 0, v5, s[44:45]
	v_mul_f32_e32 v0, v8, v0
	v_cvt_pk_bf16_f32 v5, v7, v1
	v_cvt_pk_bf16_f32 v6, v9, v10
	v_cvt_pk_bf16_f32 v7, v11, v14
	v_cndmask_b32_e64 v0, 0, v0, s[46:47]
	v_cvt_pk_bf16_f32 v8, v15, v16
	v_cvt_pk_bf16_f32 v9, v17, v18
	v_cvt_pk_bf16_f32 v10, v19, v12
	v_cvt_pk_bf16_f32 v11, v13, v0
	ds_write_b128 v115, v[4:7] offset:38912
	ds_write_b128 v115, v[8:11] offset:38928
	s_and_saveexec_b64 s[16:17], s[8:9]
	s_cbranch_execz .LBB0_1972
	v_mul_f32_e32 v0, 0x3fb8aa3b, v2
	v_exp_f32_e32 v2, v0
	s_ashr_i32 s79, s78, 31
	s_lshl_b64 s[18:19], s[78:79], 9
	v_lshl_add_u64 v[0:1], v[68:69], 0, s[18:19]
	global_store_dword v[0:1], v2, off
